# speedup vs baseline: 1.0127x; 1.0067x over previous
; __device__ __forceinline__ int crow(int r, int hi) { return (r & 3) + 8 * (r >> 2) + 4 * hi; }
; __device__ __forceinline__ void na_items(const Params& p, int l, int L, char* shm, const int tid, const int local, const int G, const int nNA) {
;     ...
;       const int kr = kr_lo + j;
;       const bool active = (kr >= r0w) && (kr < r0w + 8);
;       if (active) {
;         const char* Kc = Kl + cur * 8192; const char* Vc = Vl + cur * 8192;
;         f32x16 p0, p1;
; #pragma unroll
;         for (int r = 0; r < 16; ++r) { p0[r] = 0.f; p1[r] = 0.f; }
; #pragma unroll
;         for (int d0 = 0; d0 < 4; ++d0) {
;           bf16x8 b0 = *(const bf16x8*)(Kc + roff[d0]);
;           bf16x8 b1 = *(const bf16x8*)(Kc + roff[d0] + 4096);
;           p0 = __builtin_amdgcn_mfma_f32_32x32x16_bf16(b0, qr[d0], p0, 0, 0, 0);
;           p1 = __builtin_amdgcn_mfma_f32_32x32x16_bf16(b1, qr[d0], p1, 0, 0, 0);
;         }
;         {
;           const float* rb = rpbL + (kr - rq + 7) * 31 + (15 - qc);
; #pragma unroll
;           for (int r = 0; r < 16; ++r) {
;             const int kc = crow(r, hi);
;             const bool v0 = (kc >= c0) && (kc < c0 + 16);
;             const float b0 = rb[v0 ? kc : qc];
;             p0[r] = v0 ? p0[r] + b0 : -1e30f;
;             const int kc1 = kc + 32;
;             const bool v1 = (kc1 >= c0) && (kc1 < c0 + 16);
;             const float b1 = rb[v1 ? kc1 : qc];
;             p1[r] = v1 ? p1[r] + b1 : -1e30f;
;           }
;         }
.LBB0_447:
	s_and_b32 s97, s42, 1
	s_add_i32 s6, s99, s42
	s_cmp_ge_i32 s6, s46
	s_cselect_b64 s[42:43], -1, 0
	s_cmp_lt_i32 s6, s98
	s_cselect_b64 vcc, -1, 0
	s_and_b64 s[42:43], s[42:43], vcc
	s_andn2_b64 vcc, exec, s[42:43]
	s_cbranch_vccnz .LBB0_517
	s_lshl_b32 s6, s97, 13
	v_add_u32_e32 v236, s6, v109
	v_add_u32_e32 v237, s6, v120
	v_add_u32_e32 v240, s6, v121
	v_add_u32_e32 v241, s6, v122
	s_cmp_eq_u64 s[40:41], 0
	s_cbranch_scc1 .Lna_left
	ds_read_b128 v[220:223], v236
	ds_read_b128 v[224:227], v236 offset:4096
	ds_read_b128 v[228:231], v237
	ds_read_b128 v[232:235], v237 offset:4096
	ds_read2_b32 v[2:3], v117 offset0:24 offset1:25
	ds_read2_b32 v[4:5], v117 offset0:26 offset1:27
	v_mov_b32_e32 v244, 0xf149f2ca
	s_waitcnt lgkmcnt(5)
	v_mfma_f32_32x32x16_bf16 v[64:79], v[220:223], v[80:83], 0
	ds_read_b128 v[220:223], v240
	s_waitcnt lgkmcnt(5)
	v_mfma_f32_32x32x16_bf16 v[48:63], v[224:227], v[80:83], 0
	ds_read_b128 v[224:227], v240 offset:4096
	s_waitcnt lgkmcnt(5)
	v_mfma_f32_32x32x16_bf16 v[64:79], v[228:231], v[84:87], v[64:79]
	ds_read_b128 v[228:231], v241
	s_waitcnt lgkmcnt(5)
	v_mfma_f32_32x32x16_bf16 v[48:63], v[232:235], v[84:87], v[48:63]
	ds_read_b128 v[232:235], v241 offset:4096
	s_waitcnt lgkmcnt(3)
	v_mfma_f32_32x32x16_bf16 v[64:79], v[220:223], v[88:91], v[64:79]
	s_waitcnt lgkmcnt(2)
	v_mfma_f32_32x32x16_bf16 v[48:63], v[224:227], v[88:91], v[48:63]
	s_waitcnt lgkmcnt(1)
	v_mfma_f32_32x32x16_bf16 v[64:79], v[228:231], v[92:95], v[64:79]
	s_waitcnt lgkmcnt(0)
	v_mfma_f32_32x32x16_bf16 v[48:63], v[232:235], v[92:95], v[48:63]
	s_nop 9
	v_add_f32_e32 v76, v76, v2
	v_add_f32_e32 v77, v77, v3
	v_add_f32_e32 v78, v78, v4
	v_add_f32_e32 v79, v79, v5
	ds_read2_b32 v[2:3], v117 offset0:32 offset1:33
	ds_read2_b32 v[4:5], v117 offset0:34 offset1:35
	ds_read2_b32 v[6:7], v117 offset0:40 offset1:41
	ds_read2_b32 v[8:9], v117 offset0:42 offset1:43
	ds_read2_b32 v[10:11], v117 offset0:48 offset1:49
	ds_read2_b32 v[12:13], v117 offset0:50 offset1:51
	ds_read2_b32 v[250:251], v117 offset0:56 offset1:57
	ds_read2_b32 v[252:253], v117 offset0:58 offset1:59
	v_cndmask_b32_e64 v76, v244, v76, s[78:79]
	v_cndmask_b32_e64 v77, v244, v77, s[0:1]
	v_cndmask_b32_e64 v78, v244, v78, s[70:71]
	v_cndmask_b32_e64 v79, v244, v79, s[2:3]
	s_waitcnt lgkmcnt(0)
	v_add_f32_e32 v48, v48, v2
	v_add_f32_e32 v49, v49, v3
	v_add_f32_e32 v50, v50, v4
	v_add_f32_e32 v51, v51, v5
	v_add_f32_e32 v52, v52, v6
	v_add_f32_e32 v53, v53, v7
	v_add_f32_e32 v54, v54, v8
	v_add_f32_e32 v55, v55, v9
	v_add_f32_e32 v56, v56, v10
	v_add_f32_e32 v57, v57, v11
	v_add_f32_e32 v58, v58, v12
	v_add_f32_e32 v59, v59, v13
	v_add_f32_e32 v60, v60, v250
	v_add_f32_e32 v61, v61, v251
	v_add_f32_e32 v62, v62, v252
	v_add_f32_e32 v63, v63, v253
	ds_read_b128 v[2:5], v237 offset:16384
	ds_read_b128 v[6:9], v237 offset:20480
	ds_read_b128 v[10:13], v240 offset:16384
	ds_read_b128 v[250:253], v240 offset:20480
	v_cndmask_b32_e64 v48, v244, v48, s[90:91]
	v_cndmask_b32_e64 v49, v244, v49, s[94:95]
	v_cndmask_b32_e64 v50, v244, v50, s[44:45]
	v_cndmask_b32_e64 v51, v244, v51, s[84:85]
	v_cndmask_b32_e64 v52, v244, v52, s[86:87]
	v_cndmask_b32_e64 v53, v244, v53, s[56:57]
	v_cndmask_b32_e64 v54, v244, v54, s[62:63]
	v_cndmask_b32_e64 v55, v244, v55, s[64:65]
	v_cndmask_b32_e64 v56, v244, v56, s[24:25]
	v_cndmask_b32_e64 v57, v244, v57, s[26:27]
	v_cndmask_b32_e64 v58, v244, v58, s[28:29]
	v_cndmask_b32_e64 v59, v244, v59, s[30:31]
	v_cndmask_b32_e64 v60, v244, v60, s[34:35]
	v_cndmask_b32_e64 v61, v244, v61, s[36:37]
	v_cndmask_b32_e64 v62, v244, v62, s[38:39]
	v_cndmask_b32_e64 v63, v244, v63, s[40:41]
	v_max3_f32 v245, v76, v77, v78
	v_max3_f32 v245, v245, v79, v48
	v_max3_f32 v245, v245, v49, v50
	v_max3_f32 v245, v245, v51, v52
	v_max3_f32 v245, v245, v53, v54
	v_max3_f32 v245, v245, v55, v56
	v_max3_f32 v245, v245, v57, v58
	v_max3_f32 v245, v245, v59, v60
	v_max3_f32 v245, v245, v61, v62
	v_max_f32_e32 v245, v245, v63
	v_mov_b32_e32 v238, v245
	s_nop 1
	v_permlane32_swap_b32_e32 v245, v238
	v_max_f32_e32 v245, v245, v238
	v_sub_f32_e32 v238, v245, v210
	s_mov_b32 s6, 0x42800000
	v_cmp_ge_f32_e32 vcc, s6, v238
	v_max_f32_e32 v238, v210, v245
	v_sub_f32_e32 v243, v210, v238
	v_mul_f32_e32 v243, 0x3e38aa3b, v243
	v_exp_f32_e32 v243, v243
	s_cmp_eq_u64 vcc, exec
	s_cselect_b64 s[42:43], -1, 0
	v_cndmask_b32_e64 v243, v243, 1.0, s[42:43]
	v_cmp_gt_f32_e32 vcc, 1.0, v243
	s_cbranch_vccz .Lna_norescale_R
	s_and_saveexec_b64 vcc, s[4:5]
	ds_write_b32 v170, v243 offset:32768
	s_or_b64 exec, exec, vcc
	s_waitcnt lgkmcnt(0)
	v_add_u32_e32 v0, s82, v108
	ds_read_b128 v[220:223], v0 offset:32864
	ds_read_b128 v[224:227], v0 offset:32832
	ds_read_b128 v[228:231], v0 offset:32800
	ds_read_b128 v[232:235], v0 offset:32768
	s_waitcnt lgkmcnt(0)
	v_pk_mul_f32 v[28:29], v[28:29], v[220:221]
	v_pk_mul_f32 v[30:31], v[30:31], v[222:223]
	v_pk_mul_f32 v[24:25], v[24:25], v[224:225]
	v_pk_mul_f32 v[26:27], v[26:27], v[226:227]
	v_pk_mul_f32 v[20:21], v[20:21], v[228:229]
	v_pk_mul_f32 v[22:23], v[22:23], v[230:231]
	v_pk_mul_f32 v[16:17], v[16:17], v[232:233]
	v_pk_mul_f32 v[18:19], v[18:19], v[234:235]
	v_pk_mul_f32 v[44:45], v[44:45], v[220:221]
	v_pk_mul_f32 v[46:47], v[46:47], v[222:223]
	v_pk_mul_f32 v[40:41], v[40:41], v[224:225]
	v_pk_mul_f32 v[42:43], v[42:43], v[226:227]
	v_pk_mul_f32 v[36:37], v[36:37], v[228:229]
	v_pk_mul_f32 v[38:39], v[38:39], v[230:231]
	v_pk_mul_f32 v[32:33], v[32:33], v[232:233]
	v_pk_mul_f32 v[34:35], v[34:35], v[234:235]
; __device__ __forceinline__ void partialSM(f32x16& p0, f32x16& p1, float& m_reg, float& mn, float& alpha) {
;     ...
;   float mnC = -mn * C;
; #pragma unroll
;   for (int r = 0; r < 16; ++r) p0[r] = fmaf(p0[r], C, mnC);
; #pragma unroll
;   for (int r = 0; r < 16; ++r) p1[r] = fmaf(p1[r], C, mnC);
; #pragma unroll
;   for (int r = 0; r < 16; ++r) p0[r] = __builtin_amdgcn_exp2f(p0[r]);
; }
; __device__ __forceinline__ void finishSM(f32x16& p0, f32x16& p1, float alpha, float& l_reg, bf16x8& pa0, bf16x8& pa1, bf16x8& pa2, bf16x8& pa3) {
; #pragma unroll
;   for (int r = 0; r < 16; ++r) p1[r] = __builtin_amdgcn_exp2f(p1[r]);
;   float ps = 0;
; #pragma unroll
;   for (int r = 0; r < 16; ++r) ps += p0[r];
; #pragma unroll
;   for (int r = 0; r < 16; ++r) ps += p1[r];
; __device__ __forceinline__ void na_items(const Params& p, int l, int L, char* shm, const int tid, const int local, const int G, const int nNA) {
;     ...
;         for (int d0 = 0; d0 < 4; ++d0) {
;           bf16x8 b0 = *(const bf16x8*)(Kc + roff[d0]);
;           bf16x8 b1 = *(const bf16x8*)(Kc + roff[d0] + 4096);
;           p0 = __builtin_amdgcn_mfma_f32_32x32x16_bf16(b0, qr[d0], p0, 0, 0, 0);
;           p1 = __builtin_amdgcn_mfma_f32_32x32x16_bf16(b1, qr[d0], p1, 0, 0, 0);
;         }
;         {
;           const float* rb = rpbL + (kr - rq + 7) * 31 + (15 - qc);
; #pragma unroll
;           for (int r = 0; r < 16; ++r) {
;             const int kc = crow(r, hi);
;             const bool v0 = (kc >= c0) && (kc < c0 + 16);
;             const float b0 = rb[v0 ? kc : qc];
;             p0[r] = v0 ? p0[r] + b0 : -1e30f;
;             const int kc1 = kc + 32;
;             const bool v1 = (kc1 >= c0) && (kc1 < c0 + 16);
;             const float b1 = rb[v1 ? kc1 : qc];
;             p1[r] = v1 ? p1[r] + b1 : -1e30f;
;           }
;         }
;         float mn, alpha;
;         partialSM(p0, p1, m_reg, mn, alpha);
;         if (__any(alpha < 1.f)) {
;           if (hi == 0) wsf[r32] = alpha;
;           asm volatile("s_waitcnt lgkmcnt(0)" ::: "memory");
; #pragma unroll
;           for (int r = 0; r < 16; ++r) { const float a = wsf[crow(r, hi)]; o0[r] *= a; o1[r] *= a; }
;         }
;         bf16x8 pa0, pa1, pa2, pa3;
;         finishSM(p0, p1, alpha, l_reg, pa0, pa1, pa2, pa3);
;     ...
;         PVSTEP(pa0, 0); PVSTEP(pa1, 1); PVSTEP(pa2, 2); PVSTEP(pa3, 3);
.Lna_norescale_R:
	v_cndmask_b32_e64 v210, v238, v210, s[42:43]
	v_mul_f32_e32 v246, 0xbe38aa3b, v210
	ds_read_b128 v[220:223], v241 offset:16384
	ds_read_b128 v[224:227], v241 offset:20480
	v_fmamk_f32 v76, v76, 0x3e38aa3b, v246
	v_fmamk_f32 v77, v77, 0x3e38aa3b, v246
	v_fmamk_f32 v78, v78, 0x3e38aa3b, v246
	v_fmamk_f32 v79, v79, 0x3e38aa3b, v246
	v_exp_f32_e32 v76, v76
	v_exp_f32_e32 v77, v77
	v_exp_f32_e32 v78, v78
	v_exp_f32_e32 v79, v79
	v_mov_b32_e32 v216, 0
	v_mov_b32_e32 v217, 0
	v_cvt_pk_bf16_f32 v218, v76, v77
	v_cvt_pk_bf16_f32 v219, v78, v79
	s_nop 1
	v_permlane32_swap_b32_e32 v216, v218
	v_permlane32_swap_b32_e32 v217, v219
	v_add_f32_e32 v249, v77, v76
	v_add_f32_e32 v249, v78, v249
	v_add_f32_e32 v249, v79, v249
	s_waitcnt lgkmcnt(5)
	v_mfma_f32_32x32x16_bf16 v[16:31], v[216:219], v[2:5], v[16:31]
	v_fmamk_f32 v48, v48, 0x3e38aa3b, v246
	v_fmamk_f32 v49, v49, 0x3e38aa3b, v246
	v_fmamk_f32 v50, v50, 0x3e38aa3b, v246
	v_fmamk_f32 v51, v51, 0x3e38aa3b, v246
	v_fmamk_f32 v52, v52, 0x3e38aa3b, v246
	v_fmamk_f32 v53, v53, 0x3e38aa3b, v246
	v_fmamk_f32 v54, v54, 0x3e38aa3b, v246
	v_fmamk_f32 v55, v55, 0x3e38aa3b, v246
	v_fmamk_f32 v56, v56, 0x3e38aa3b, v246
	v_fmamk_f32 v57, v57, 0x3e38aa3b, v246
	v_fmamk_f32 v58, v58, 0x3e38aa3b, v246
	v_fmamk_f32 v59, v59, 0x3e38aa3b, v246
	v_fmamk_f32 v60, v60, 0x3e38aa3b, v246
	v_fmamk_f32 v61, v61, 0x3e38aa3b, v246
	v_fmamk_f32 v62, v62, 0x3e38aa3b, v246
	v_fmamk_f32 v63, v63, 0x3e38aa3b, v246
	s_waitcnt lgkmcnt(4)
	v_mfma_f32_32x32x16_bf16 v[32:47], v[216:219], v[6:9], v[32:47]
	v_exp_f32_e32 v48, v48
	v_exp_f32_e32 v49, v49
	v_exp_f32_e32 v50, v50
	v_exp_f32_e32 v51, v51
	v_exp_f32_e32 v52, v52
	v_exp_f32_e32 v53, v53
	v_exp_f32_e32 v54, v54
	v_exp_f32_e32 v55, v55
	v_exp_f32_e32 v56, v56
	v_exp_f32_e32 v57, v57
	v_exp_f32_e32 v58, v58
	v_exp_f32_e32 v59, v59
	v_exp_f32_e32 v60, v60
	v_exp_f32_e32 v61, v61
	v_exp_f32_e32 v62, v62
	v_exp_f32_e32 v63, v63
	v_cvt_pk_bf16_f32 v72, v48, v49
	v_cvt_pk_bf16_f32 v73, v50, v51
	v_cvt_pk_bf16_f32 v74, v52, v53
	v_cvt_pk_bf16_f32 v75, v54, v55
	v_cvt_pk_bf16_f32 v76, v56, v57
	v_cvt_pk_bf16_f32 v77, v58, v59
	v_cvt_pk_bf16_f32 v78, v60, v61
	v_cvt_pk_bf16_f32 v79, v62, v63
	s_nop 1
	v_permlane32_swap_b32_e32 v72, v74
	v_permlane32_swap_b32_e32 v73, v75
	v_permlane32_swap_b32_e32 v76, v78
	v_permlane32_swap_b32_e32 v77, v79
	v_add_f32_e32 v249, v48, v249
	v_add_f32_e32 v249, v49, v249
	s_waitcnt lgkmcnt(3)
	v_mfma_f32_32x32x16_bf16 v[16:31], v[72:75], v[10:13], v[16:31]
	v_add_f32_e32 v249, v50, v249
	v_add_f32_e32 v249, v51, v249
	v_add_f32_e32 v249, v52, v249
	s_waitcnt lgkmcnt(2)
	v_mfma_f32_32x32x16_bf16 v[32:47], v[72:75], v[250:253], v[32:47]
	v_add_f32_e32 v249, v53, v249
	v_add_f32_e32 v249, v54, v249
	v_add_f32_e32 v249, v55, v249
	v_add_f32_e32 v249, v56, v249
	s_waitcnt lgkmcnt(1)
	v_mfma_f32_32x32x16_bf16 v[16:31], v[76:79], v[220:223], v[16:31]
	v_add_f32_e32 v249, v57, v249
	v_add_f32_e32 v249, v58, v249
	v_add_f32_e32 v249, v59, v249
	s_waitcnt lgkmcnt(0)
	v_mfma_f32_32x32x16_bf16 v[32:47], v[76:79], v[224:227], v[32:47]
	v_add_f32_e32 v249, v60, v249
	v_add_f32_e32 v249, v61, v249
	v_add_f32_e32 v249, v62, v249
	v_add_f32_e32 v249, v63, v249
	v_mov_b32_e32 v238, v249
	s_nop 1
	v_permlane32_swap_b32_e32 v249, v238
	v_add_f32_e32 v0, v249, v238
	v_fmac_f32_e32 v0, v209, v243
	v_mov_b32_e32 v209, v0
	s_branch .Lna_blkend
.Lna_left:
	ds_read_b128 v[220:223], v236
	ds_read_b128 v[224:227], v236 offset:4096
	ds_read_b128 v[228:231], v237
	ds_read_b128 v[232:235], v237 offset:4096
	ds_read2_b32 v[2:3], v117 offset1:1
	ds_read2_b32 v[4:5], v117 offset0:2 offset1:3
	ds_read2_b32 v[6:7], v117 offset0:8 offset1:9
	ds_read2_b32 v[8:9], v117 offset0:10 offset1:11
	ds_read2_b32 v[10:11], v117 offset0:16 offset1:17
	ds_read2_b32 v[12:13], v117 offset0:18 offset1:19
	ds_read2_b32 v[250:251], v117 offset0:24 offset1:25
	ds_read2_b32 v[252:253], v117 offset0:26 offset1:27
	v_mov_b32_e32 v244, 0xf149f2ca
	s_waitcnt lgkmcnt(11)
	v_mfma_f32_32x32x16_bf16 v[64:79], v[220:223], v[80:83], 0
	ds_read_b128 v[220:223], v240
	s_waitcnt lgkmcnt(11)
	v_mfma_f32_32x32x16_bf16 v[48:63], v[224:227], v[80:83], 0
	ds_read_b128 v[224:227], v240 offset:4096
	s_waitcnt lgkmcnt(11)
	v_mfma_f32_32x32x16_bf16 v[64:79], v[228:231], v[84:87], v[64:79]
	ds_read_b128 v[228:231], v241
	s_waitcnt lgkmcnt(11)
	v_mfma_f32_32x32x16_bf16 v[48:63], v[232:235], v[84:87], v[48:63]
	ds_read_b128 v[232:235], v241 offset:4096
	s_waitcnt lgkmcnt(3)
	v_mfma_f32_32x32x16_bf16 v[64:79], v[220:223], v[88:91], v[64:79]
	s_waitcnt lgkmcnt(2)
	v_mfma_f32_32x32x16_bf16 v[48:63], v[224:227], v[88:91], v[48:63]
	s_waitcnt lgkmcnt(1)
	v_mfma_f32_32x32x16_bf16 v[64:79], v[228:231], v[92:95], v[64:79]
	s_waitcnt lgkmcnt(0)
	v_mfma_f32_32x32x16_bf16 v[48:63], v[232:235], v[92:95], v[48:63]
	s_nop 9
	v_add_f32_e32 v64, v64, v2
	v_add_f32_e32 v65, v65, v3
	v_add_f32_e32 v66, v66, v4
	v_add_f32_e32 v67, v67, v5
	v_add_f32_e32 v68, v68, v6
	v_add_f32_e32 v69, v69, v7
	v_add_f32_e32 v70, v70, v8
	v_add_f32_e32 v71, v71, v9
	v_add_f32_e32 v72, v72, v10
	v_add_f32_e32 v73, v73, v11
	v_add_f32_e32 v74, v74, v12
	v_add_f32_e32 v75, v75, v13
	v_add_f32_e32 v76, v76, v250
	v_add_f32_e32 v77, v77, v251
	v_add_f32_e32 v78, v78, v252
	v_add_f32_e32 v79, v79, v253
	ds_read2_b32 v[2:3], v117 offset0:32 offset1:33
	ds_read2_b32 v[4:5], v117 offset0:34 offset1:35
	v_cndmask_b32_e64 v64, v244, v64, s[8:9]
	v_cndmask_b32_e64 v65, v244, v65, s[10:11]
	v_cndmask_b32_e64 v66, v244, v66, s[12:13]
	v_cndmask_b32_e64 v67, v244, v67, s[14:15]
	v_cndmask_b32_e64 v68, v244, v68, s[16:17]
	v_cndmask_b32_e64 v69, v244, v69, s[18:19]
	v_cndmask_b32_e64 v70, v244, v70, s[20:21]
	v_cndmask_b32_e64 v71, v244, v71, s[22:23]
	v_cndmask_b32_e64 v72, v244, v72, s[66:67]
	v_cndmask_b32_e64 v73, v244, v73, s[68:69]
	v_cndmask_b32_e64 v74, v244, v74, s[72:73]
	v_cndmask_b32_e64 v75, v244, v75, s[74:75]
	v_cndmask_b32_e64 v76, v244, v76, s[78:79]
	v_cndmask_b32_e64 v77, v244, v77, s[0:1]
	v_cndmask_b32_e64 v78, v244, v78, s[70:71]
	v_cndmask_b32_e64 v79, v244, v79, s[2:3]
	s_waitcnt lgkmcnt(0)
; __device__ __forceinline__ void partialSM(f32x16& p0, f32x16& p1, float& m_reg, float& mn, float& alpha) {
;   constexpr float C = SCALE * 1.4426950408889634f;
;   float pmax = p0[0];
; #pragma unroll
;   for (int r = 1; r < 16; ++r) pmax = fmaxf(pmax, p0[r]);
; #pragma unroll
;   for (int r = 0; r < 16; ++r) pmax = fmaxf(pmax, p1[r]);
;   { auto rr = __builtin_amdgcn_permlane32_swap(__float_as_uint(pmax), __float_as_uint(pmax), false, false);
;     pmax = fmaxf(__uint_as_float(rr[0]), __uint_as_float(rr[1])); }
;   if (__builtin_expect(__all(pmax - m_reg <= THR / SCALE), 1)) { mn = m_reg; alpha = 1.f; }
;   else { mn = fmaxf(m_reg, pmax); alpha = __builtin_amdgcn_exp2f((m_reg - mn) * C); m_reg = mn; }
;   float mnC = -mn * C;
; #pragma unroll
;   for (int r = 0; r < 16; ++r) p0[r] = fmaf(p0[r], C, mnC);
; #pragma unroll
;   for (int r = 0; r < 16; ++r) p1[r] = fmaf(p1[r], C, mnC);
; #pragma unroll
;   for (int r = 0; r < 16; ++r) p0[r] = __builtin_amdgcn_exp2f(p0[r]);
; }
; __device__ __forceinline__ void finishSM(f32x16& p0, f32x16& p1, float alpha, float& l_reg, bf16x8& pa0, bf16x8& pa1, bf16x8& pa2, bf16x8& pa3) {
; #pragma unroll
;   for (int r = 0; r < 16; ++r) p1[r] = __builtin_amdgcn_exp2f(p1[r]);
;   float ps = 0;
; #pragma unroll
;   for (int r = 0; r < 16; ++r) ps += p0[r];
; #pragma unroll
;   for (int r = 0; r < 16; ++r) ps += p1[r];
;   { auto rr = __builtin_amdgcn_permlane32_swap(__float_as_uint(ps), __float_as_uint(ps), false, false);
;     ps = __uint_as_float(rr[0]) + __uint_as_float(rr[1]); }
;   l_reg = l_reg * alpha + ps;
;     ...
;   PK4(p0, 0, pa0); PK4(p0, 8, pa1); PK4(p1, 0, pa2); PK4(p1, 8, pa3);
; __device__ __forceinline__ void na_items(const Params& p, int l, int L, char* shm, const int tid, const int local, const int G, const int nNA) {
;     ...
;         PVSTEP(pa0, 0); PVSTEP(pa1, 1); PVSTEP(pa2, 2); PVSTEP(pa3, 3);
	v_add_f32_e32 v48, v48, v2
	v_add_f32_e32 v49, v49, v3
	v_add_f32_e32 v50, v50, v4
	v_add_f32_e32 v51, v51, v5
	ds_read_b128 v[2:5], v236 offset:16384
	ds_read_b128 v[6:9], v236 offset:20480
	ds_read_b128 v[10:13], v237 offset:16384
	ds_read_b128 v[250:253], v237 offset:20480
	v_cndmask_b32_e64 v48, v244, v48, s[90:91]
	v_cndmask_b32_e64 v49, v244, v49, s[94:95]
	v_cndmask_b32_e64 v50, v244, v50, s[44:45]
	v_cndmask_b32_e64 v51, v244, v51, s[84:85]
	v_max3_f32 v245, v64, v65, v66
	v_max3_f32 v245, v245, v67, v68
	v_max3_f32 v245, v245, v69, v70
	v_max3_f32 v245, v245, v71, v72
	v_max3_f32 v245, v245, v73, v74
	v_max3_f32 v245, v245, v75, v76
	v_max3_f32 v245, v245, v77, v78
	v_max3_f32 v245, v245, v79, v48
	v_max3_f32 v245, v245, v49, v50
	v_max_f32_e32 v245, v245, v51
	v_mov_b32_e32 v238, v245
	s_nop 1
	v_permlane32_swap_b32_e32 v245, v238
	v_max_f32_e32 v245, v245, v238
	v_sub_f32_e32 v238, v245, v210
	s_mov_b32 s6, 0x42800000
	v_cmp_ge_f32_e32 vcc, s6, v238
	v_max_f32_e32 v238, v210, v245
	v_sub_f32_e32 v243, v210, v238
	v_mul_f32_e32 v243, 0x3e38aa3b, v243
	v_exp_f32_e32 v243, v243
	s_cmp_eq_u64 vcc, exec
	s_cselect_b64 s[42:43], -1, 0
	v_cndmask_b32_e64 v243, v243, 1.0, s[42:43]
	v_cmp_gt_f32_e32 vcc, 1.0, v243
	s_cbranch_vccz .Lna_norescale_L
	s_and_saveexec_b64 vcc, s[4:5]
	ds_write_b32 v170, v243 offset:32768
	s_or_b64 exec, exec, vcc
	s_waitcnt lgkmcnt(0)
	v_add_u32_e32 v0, s82, v108
	ds_read_b128 v[220:223], v0 offset:32864
	ds_read_b128 v[224:227], v0 offset:32832
	ds_read_b128 v[228:231], v0 offset:32800
	ds_read_b128 v[232:235], v0 offset:32768
	s_waitcnt lgkmcnt(0)
	v_pk_mul_f32 v[28:29], v[28:29], v[220:221]
	v_pk_mul_f32 v[30:31], v[30:31], v[222:223]
	v_pk_mul_f32 v[24:25], v[24:25], v[224:225]
	v_pk_mul_f32 v[26:27], v[26:27], v[226:227]
	v_pk_mul_f32 v[20:21], v[20:21], v[228:229]
	v_pk_mul_f32 v[22:23], v[22:23], v[230:231]
	v_pk_mul_f32 v[16:17], v[16:17], v[232:233]
	v_pk_mul_f32 v[18:19], v[18:19], v[234:235]
	v_pk_mul_f32 v[44:45], v[44:45], v[220:221]
	v_pk_mul_f32 v[46:47], v[46:47], v[222:223]
	v_pk_mul_f32 v[40:41], v[40:41], v[224:225]
	v_pk_mul_f32 v[42:43], v[42:43], v[226:227]
	v_pk_mul_f32 v[36:37], v[36:37], v[228:229]
	v_pk_mul_f32 v[38:39], v[38:39], v[230:231]
	v_pk_mul_f32 v[32:33], v[32:33], v[232:233]
	v_pk_mul_f32 v[34:35], v[34:35], v[234:235]
.Lna_norescale_L:
	v_cndmask_b32_e64 v210, v238, v210, s[42:43]
	v_mul_f32_e32 v246, 0xbe38aa3b, v210
	ds_read_b128 v[220:223], v240 offset:16384
	ds_read_b128 v[224:227], v240 offset:20480
	v_fmamk_f32 v64, v64, 0x3e38aa3b, v246
	v_fmamk_f32 v65, v65, 0x3e38aa3b, v246
	v_fmamk_f32 v66, v66, 0x3e38aa3b, v246
	v_fmamk_f32 v67, v67, 0x3e38aa3b, v246
	v_fmamk_f32 v68, v68, 0x3e38aa3b, v246
	v_fmamk_f32 v69, v69, 0x3e38aa3b, v246
	v_fmamk_f32 v70, v70, 0x3e38aa3b, v246
	v_fmamk_f32 v71, v71, 0x3e38aa3b, v246
	v_fmamk_f32 v72, v72, 0x3e38aa3b, v246
	v_fmamk_f32 v73, v73, 0x3e38aa3b, v246
	v_fmamk_f32 v74, v74, 0x3e38aa3b, v246
	v_fmamk_f32 v75, v75, 0x3e38aa3b, v246
	v_fmamk_f32 v76, v76, 0x3e38aa3b, v246
	v_fmamk_f32 v77, v77, 0x3e38aa3b, v246
	v_fmamk_f32 v78, v78, 0x3e38aa3b, v246
	v_fmamk_f32 v79, v79, 0x3e38aa3b, v246
	v_exp_f32_e32 v64, v64
	v_exp_f32_e32 v65, v65
	v_exp_f32_e32 v66, v66
	v_exp_f32_e32 v67, v67
	v_exp_f32_e32 v68, v68
	v_exp_f32_e32 v69, v69
	v_exp_f32_e32 v70, v70
	v_exp_f32_e32 v71, v71
	v_exp_f32_e32 v72, v72
	v_exp_f32_e32 v73, v73
	v_exp_f32_e32 v74, v74
	v_exp_f32_e32 v75, v75
	v_exp_f32_e32 v76, v76
	v_exp_f32_e32 v77, v77
	v_exp_f32_e32 v78, v78
	v_exp_f32_e32 v79, v79
	v_cvt_pk_bf16_f32 v212, v64, v65
	v_cvt_pk_bf16_f32 v213, v66, v67
	v_cvt_pk_bf16_f32 v214, v68, v69
	v_cvt_pk_bf16_f32 v215, v70, v71
	v_cvt_pk_bf16_f32 v216, v72, v73
	v_cvt_pk_bf16_f32 v217, v74, v75
	v_cvt_pk_bf16_f32 v218, v76, v77
	v_cvt_pk_bf16_f32 v219, v78, v79
	s_nop 1
	v_permlane32_swap_b32_e32 v212, v214
	v_permlane32_swap_b32_e32 v213, v215
	v_permlane32_swap_b32_e32 v216, v218
	v_permlane32_swap_b32_e32 v217, v219
	v_add_f32_e32 v249, v65, v64
	v_add_f32_e32 v249, v66, v249
	v_add_f32_e32 v249, v67, v249
	v_add_f32_e32 v249, v68, v249
	v_add_f32_e32 v249, v69, v249
	v_add_f32_e32 v249, v70, v249
	v_add_f32_e32 v249, v71, v249
	v_add_f32_e32 v249, v72, v249
	v_add_f32_e32 v249, v73, v249
	v_add_f32_e32 v249, v74, v249
	v_add_f32_e32 v249, v75, v249
	v_add_f32_e32 v249, v76, v249
	v_add_f32_e32 v249, v77, v249
	v_add_f32_e32 v249, v78, v249
	v_add_f32_e32 v249, v79, v249
	s_waitcnt lgkmcnt(5)
	v_mfma_f32_32x32x16_bf16 v[16:31], v[212:215], v[2:5], v[16:31]
	v_fmamk_f32 v48, v48, 0x3e38aa3b, v246
	v_fmamk_f32 v49, v49, 0x3e38aa3b, v246
	s_waitcnt lgkmcnt(4)
	v_mfma_f32_32x32x16_bf16 v[32:47], v[212:215], v[6:9], v[32:47]
	v_fmamk_f32 v50, v50, 0x3e38aa3b, v246
	v_fmamk_f32 v51, v51, 0x3e38aa3b, v246
	s_waitcnt lgkmcnt(3)
	v_mfma_f32_32x32x16_bf16 v[16:31], v[216:219], v[10:13], v[16:31]
	v_exp_f32_e32 v48, v48
	v_exp_f32_e32 v49, v49
	s_waitcnt lgkmcnt(2)
	v_mfma_f32_32x32x16_bf16 v[32:47], v[216:219], v[250:253], v[32:47]
	v_exp_f32_e32 v50, v50
	v_exp_f32_e32 v51, v51
	v_cvt_pk_bf16_f32 v72, v48, v49
	v_cvt_pk_bf16_f32 v73, v50, v51
	v_mov_b32_e32 v74, 0
	v_mov_b32_e32 v75, 0
	s_nop 1
	v_permlane32_swap_b32_e32 v72, v74
	v_permlane32_swap_b32_e32 v73, v75
	v_add_f32_e32 v249, v48, v249
	v_add_f32_e32 v249, v49, v249
	s_waitcnt lgkmcnt(1)
	v_mfma_f32_32x32x16_bf16 v[16:31], v[72:75], v[220:223], v[16:31]
	v_add_f32_e32 v249, v50, v249
	s_waitcnt lgkmcnt(0)
	v_mfma_f32_32x32x16_bf16 v[32:47], v[72:75], v[224:227], v[32:47]
	v_add_f32_e32 v249, v51, v249
	v_mov_b32_e32 v238, v249
	s_nop 1
	v_permlane32_swap_b32_e32 v249, v238
	v_add_f32_e32 v0, v249, v238
	v_fmac_f32_e32 v0, v209, v243
	v_mov_b32_e32 v209, v0
.Lna_blkend:
.LBB0_517:
	s_andn2_b64 vcc, exec, s[80:81]
	s_cbranch_vccnz .LBB0_519
	s_lshl_b32 s6, s97, 13
	s_xor_b32 s6, s6, 0x2000
	v_add_u32_e32 v0, s6, v167
	s_waitcnt vmcnt(1)
	ds_write_b128 v0, v[96:99]
	s_waitcnt vmcnt(0)
	ds_write_b128 v0, v[100:103] offset:16384
